# attention loop restructured: softmax VALU spread across both S and PV MFMA streams per wave (k-major PV for map0), 4 specialised paths
# speedup vs baseline: 1.0088x; 1.0057x over previous
.Lat_e_nokw:
	s_and_b64 vcc, exec, s[38:39]
	s_cbranch_vccnz .LBB0_300
	v_add_u32_e32 v239, s11, v234
	v_add_u32_e32 v238, s10, v234
	ds_read_b64_tr_b16 v[128:129], v239
	ds_read_b64_tr_b16 v[130:131], v239 offset:512
	ds_read_b64_tr_b16 v[132:133], v239 offset:1024
	ds_read_b64_tr_b16 v[134:135], v239 offset:1536
	ds_read_b64_tr_b16 v[136:137], v239 offset:2048
	ds_read_b64_tr_b16 v[138:139], v239 offset:2560
	ds_read_b64_tr_b16 v[140:141], v239 offset:3072
	ds_read_b64_tr_b16 v[142:143], v239 offset:3584
	v_exp_f32_e32 v80, v80
	v_exp_f32_e32 v81, v81
	v_exp_f32_e32 v82, v82
	v_add_f32_e32 v0, 0, v80
	v_exp_f32_e32 v83, v83
	v_add_f32_e32 v0, v81, v0
	v_exp_f32_e32 v84, v84
	v_add_f32_e32 v0, v82, v0
	v_exp_f32_e32 v85, v85
	v_add_f32_e32 v0, v83, v0
	s_waitcnt lgkmcnt(6)
	v_mfma_f32_32x32x16_bf16 v[64:79], v[128:131], v[112:115], v[64:79]
	v_exp_f32_e32 v86, v86
	v_add_f32_e32 v0, v84, v0
	v_exp_f32_e32 v87, v87
	s_waitcnt lgkmcnt(4)
	v_mfma_f32_32x32x16_bf16 v[64:79], v[132:135], v[116:119], v[64:79]
	ds_read_b64_tr_b16 v[176:177], v239 offset:4096
	ds_read_b64_tr_b16 v[178:179], v239 offset:4608
	ds_read_b64_tr_b16 v[180:181], v239 offset:5120
	ds_read_b64_tr_b16 v[182:183], v239 offset:5632
	v_add_f32_e32 v0, v85, v0
	v_exp_f32_e32 v88, v88
	v_add_f32_e32 v0, v86, v0
	s_waitcnt lgkmcnt(6)
	v_mfma_f32_32x32x16_bf16 v[64:79], v[136:139], v[120:123], v[64:79]
	v_exp_f32_e32 v89, v89
	v_add_f32_e32 v0, v87, v0
	v_exp_f32_e32 v90, v90
	s_waitcnt lgkmcnt(4)
	v_mfma_f32_32x32x16_bf16 v[64:79], v[140:143], v[124:127], v[64:79]
	ds_read_b64_tr_b16 v[128:129], v239 offset:6144
	ds_read_b64_tr_b16 v[130:131], v239 offset:6656
	ds_read_b64_tr_b16 v[132:133], v239 offset:7168
	ds_read_b64_tr_b16 v[134:135], v239 offset:7680
	v_add_f32_e32 v0, v88, v0
	v_exp_f32_e32 v91, v91
	v_add_f32_e32 v0, v89, v0
	s_waitcnt lgkmcnt(6)
	v_mfma_f32_32x32x16_bf16 v[48:63], v[176:179], v[112:115], v[48:63]
	v_exp_f32_e32 v92, v92
	v_add_f32_e32 v0, v90, v0
	v_exp_f32_e32 v93, v93
	s_waitcnt lgkmcnt(4)
	v_mfma_f32_32x32x16_bf16 v[48:63], v[180:183], v[116:119], v[48:63]
	ds_read_b64_tr_b16 v[136:137], v239 offset:8192
	ds_read_b64_tr_b16 v[138:139], v239 offset:8704
	ds_read_b64_tr_b16 v[140:141], v239 offset:9216
	ds_read_b64_tr_b16 v[142:143], v239 offset:9728
	v_add_f32_e32 v0, v91, v0
	v_exp_f32_e32 v94, v94
	v_add_f32_e32 v0, v92, v0
	s_waitcnt lgkmcnt(6)
	v_mfma_f32_32x32x16_bf16 v[48:63], v[128:131], v[120:123], v[48:63]
	v_exp_f32_e32 v95, v95
	v_add_f32_e32 v0, v93, v0
	v_add_f32_e32 v0, v94, v0
	s_waitcnt lgkmcnt(4)
	v_mfma_f32_32x32x16_bf16 v[48:63], v[132:135], v[124:127], v[48:63]
	ds_read_b64_tr_b16 v[176:177], v239 offset:10240
	ds_read_b64_tr_b16 v[178:179], v239 offset:10752
	ds_read_b64_tr_b16 v[180:181], v239 offset:11264
	ds_read_b64_tr_b16 v[182:183], v239 offset:11776
	v_add_f32_e32 v0, v95, v0
	v_cvt_pk_bf16_f32 v188, v80, v81
	v_cvt_pk_bf16_f32 v189, v82, v83
	s_waitcnt lgkmcnt(6)
	v_mfma_f32_32x32x16_bf16 v[32:47], v[136:139], v[112:115], v[32:47]
	v_cvt_pk_bf16_f32 v190, v84, v85
	v_cvt_pk_bf16_f32 v191, v86, v87
	v_cvt_pk_bf16_f32 v192, v88, v89
	s_waitcnt lgkmcnt(4)
	v_mfma_f32_32x32x16_bf16 v[32:47], v[140:143], v[116:119], v[32:47]
	ds_read_b64_tr_b16 v[128:129], v239 offset:12288
	ds_read_b64_tr_b16 v[130:131], v239 offset:12800
	ds_read_b64_tr_b16 v[132:133], v239 offset:13312
	ds_read_b64_tr_b16 v[134:135], v239 offset:13824
	v_cvt_pk_bf16_f32 v193, v90, v91
	v_cvt_pk_bf16_f32 v194, v92, v93
	v_cvt_pk_bf16_f32 v195, v94, v95
	s_waitcnt lgkmcnt(6)
	v_mfma_f32_32x32x16_bf16 v[32:47], v[176:179], v[120:123], v[32:47]
	v_exp_f32_e32 v96, v96
	v_exp_f32_e32 v97, v97
	v_exp_f32_e32 v98, v98
	s_waitcnt lgkmcnt(4)
	v_mfma_f32_32x32x16_bf16 v[32:47], v[180:183], v[124:127], v[32:47]
	ds_read_b64_tr_b16 v[136:137], v239 offset:14336
	ds_read_b64_tr_b16 v[138:139], v239 offset:14848
	ds_read_b64_tr_b16 v[140:141], v239 offset:15360
	ds_read_b64_tr_b16 v[142:143], v239 offset:15872
	v_add_f32_e32 v0, v96, v0
	v_exp_f32_e32 v99, v99
	v_add_f32_e32 v0, v97, v0
	s_waitcnt lgkmcnt(6)
	v_mfma_f32_32x32x16_bf16 v[16:31], v[128:131], v[112:115], v[16:31]
	v_exp_f32_e32 v100, v100
	v_add_f32_e32 v0, v98, v0
	v_exp_f32_e32 v101, v101
	s_waitcnt lgkmcnt(4)
	v_mfma_f32_32x32x16_bf16 v[16:31], v[132:135], v[116:119], v[16:31]
	v_add_f32_e32 v0, v99, v0
	v_exp_f32_e32 v102, v102
	v_add_f32_e32 v0, v100, v0
	s_waitcnt lgkmcnt(2)
	v_mfma_f32_32x32x16_bf16 v[16:31], v[136:139], v[120:123], v[16:31]
	v_exp_f32_e32 v103, v103
	v_add_f32_e32 v0, v101, v0
	v_exp_f32_e32 v104, v104
	s_waitcnt lgkmcnt(0)
	v_mfma_f32_32x32x16_bf16 v[16:31], v[140:143], v[124:127], v[16:31]
	v_add_f32_e32 v0, v102, v0
	v_exp_f32_e32 v105, v105
	v_add_f32_e32 v0, v103, v0
	ds_read_b128 v[112:115], v229 offset:16384
	ds_read_b128 v[128:131], v229 offset:20480
	ds_read_b128 v[240:243], v230 offset:16384
	ds_read_b128 v[244:247], v230 offset:20480
	ds_read_b128 v[248:251], v231 offset:16384
	v_exp_f32_e32 v106, v106
	v_add_f32_e32 v0, v104, v0
	s_waitcnt lgkmcnt(4)
	v_mfma_f32_32x32x16_bf16 v[112:127], v[112:115], v[160:163], 0
	v_exp_f32_e32 v107, v107
	v_add_f32_e32 v0, v105, v0
	v_exp_f32_e32 v108, v108
	s_waitcnt lgkmcnt(3)
	v_mfma_f32_32x32x16_bf16 v[128:143], v[128:131], v[160:163], 0
	v_add_f32_e32 v0, v106, v0
	v_exp_f32_e32 v109, v109
	v_add_f32_e32 v0, v107, v0
	s_waitcnt lgkmcnt(2)
	v_mfma_f32_32x32x16_bf16 v[112:127], v[240:243], v[164:167], v[112:127]
	ds_read_b128 v[240:243], v231 offset:20480
	v_exp_f32_e32 v110, v110
	v_add_f32_e32 v0, v108, v0
	v_exp_f32_e32 v111, v111
	s_waitcnt lgkmcnt(2)
	v_mfma_f32_32x32x16_bf16 v[128:143], v[244:247], v[164:167], v[128:143]
	ds_read_b128 v[244:247], v232 offset:16384
	v_add_f32_e32 v0, v109, v0
	v_add_f32_e32 v0, v110, v0
	v_add_f32_e32 v0, v111, v0
	s_waitcnt lgkmcnt(2)
	v_mfma_f32_32x32x16_bf16 v[112:127], v[248:251], v[168:171], v[112:127]
	ds_read_b128 v[248:251], v232 offset:20480
	v_cvt_pk_bf16_f32 v196, v96, v97
	v_cvt_pk_bf16_f32 v197, v98, v99
	s_waitcnt lgkmcnt(2)
	v_mfma_f32_32x32x16_bf16 v[128:143], v[240:243], v[168:171], v[128:143]
	v_cvt_pk_bf16_f32 v198, v100, v101
	v_cvt_pk_bf16_f32 v199, v102, v103
	s_waitcnt lgkmcnt(1)
	v_mfma_f32_32x32x16_bf16 v[112:127], v[244:247], v[172:175], v[112:127]
	v_cvt_pk_bf16_f32 v200, v104, v105
	v_cvt_pk_bf16_f32 v201, v106, v107
	s_waitcnt lgkmcnt(0)
	v_mfma_f32_32x32x16_bf16 v[128:143], v[248:251], v[172:175], v[128:143]
	v_cvt_pk_bf16_f32 v202, v108, v109
	v_cvt_pk_bf16_f32 v203, v110, v111
	s_branch .LBB0_304

.LBB0_300:
	v_add_u32_e32 v238, s10, v234
	ds_read_b64_tr_b16 v[176:177], v238
	ds_read_b64_tr_b16 v[178:179], v238 offset:512
	ds_read_b64_tr_b16 v[180:181], v238 offset:1024
	ds_read_b64_tr_b16 v[182:183], v238 offset:1536
	ds_read_b128 v[112:115], v229 offset:16384
	ds_read_b128 v[128:131], v229 offset:20480
	ds_read_b128 v[240:243], v230 offset:16384
	ds_read_b128 v[244:247], v230 offset:20480
	ds_read_b128 v[248:251], v231 offset:16384
	v_exp_f32_e32 v80, v80
	v_exp_f32_e32 v81, v81
	v_exp_f32_e32 v82, v82
	v_add_f32_e32 v0, 0, v80
	v_exp_f32_e32 v83, v83
	v_add_f32_e32 v0, v81, v0
	v_exp_f32_e32 v84, v84
	v_add_f32_e32 v0, v82, v0
	s_waitcnt lgkmcnt(4)
	v_mfma_f32_32x32x16_bf16 v[112:127], v[112:115], v[160:163], 0
	v_exp_f32_e32 v85, v85
	v_add_f32_e32 v0, v83, v0
	v_exp_f32_e32 v86, v86
	v_add_f32_e32 v0, v84, v0
	s_waitcnt lgkmcnt(3)
	v_mfma_f32_32x32x16_bf16 v[128:143], v[128:131], v[160:163], 0
	v_exp_f32_e32 v87, v87
	v_add_f32_e32 v0, v85, v0
	v_exp_f32_e32 v88, v88
	v_add_f32_e32 v0, v86, v0
	s_waitcnt lgkmcnt(2)
	v_mfma_f32_32x32x16_bf16 v[112:127], v[240:243], v[164:167], v[112:127]
	ds_read_b128 v[240:243], v231 offset:20480
	v_exp_f32_e32 v89, v89
	v_add_f32_e32 v0, v87, v0
	v_exp_f32_e32 v90, v90
	v_add_f32_e32 v0, v88, v0
	s_waitcnt lgkmcnt(2)
	v_mfma_f32_32x32x16_bf16 v[128:143], v[244:247], v[164:167], v[128:143]
	ds_read_b128 v[244:247], v232 offset:16384
	v_exp_f32_e32 v91, v91
	v_add_f32_e32 v0, v89, v0
	v_exp_f32_e32 v92, v92
	v_add_f32_e32 v0, v90, v0
	s_waitcnt lgkmcnt(2)
	v_mfma_f32_32x32x16_bf16 v[112:127], v[248:251], v[168:171], v[112:127]
	ds_read_b128 v[248:251], v232 offset:20480
	v_exp_f32_e32 v93, v93
	v_add_f32_e32 v0, v91, v0
	v_exp_f32_e32 v94, v94
	v_add_f32_e32 v0, v92, v0
	s_waitcnt lgkmcnt(2)
	v_mfma_f32_32x32x16_bf16 v[128:143], v[240:243], v[168:171], v[128:143]
	v_exp_f32_e32 v95, v95
	v_add_f32_e32 v0, v93, v0
	v_add_f32_e32 v0, v94, v0
	v_add_f32_e32 v0, v95, v0
	s_waitcnt lgkmcnt(1)
	v_mfma_f32_32x32x16_bf16 v[112:127], v[244:247], v[172:175], v[112:127]
	v_cvt_pk_bf16_f32 v188, v80, v81
	v_cvt_pk_bf16_f32 v189, v82, v83
	v_cvt_pk_bf16_f32 v190, v84, v85
	v_cvt_pk_bf16_f32 v191, v86, v87
	s_waitcnt lgkmcnt(0)
	v_mfma_f32_32x32x16_bf16 v[128:143], v[248:251], v[172:175], v[128:143]
	v_cvt_pk_bf16_f32 v192, v88, v89
	v_cvt_pk_bf16_f32 v193, v90, v91
	v_cvt_pk_bf16_f32 v194, v92, v93
	v_cvt_pk_bf16_f32 v195, v94, v95
	ds_read_b64_tr_b16 v[240:241], v238 offset:4096
	ds_read_b64_tr_b16 v[242:243], v238 offset:4608
	ds_read_b64_tr_b16 v[244:245], v238 offset:5120
	ds_read_b64_tr_b16 v[246:247], v238 offset:5632
	s_waitcnt lgkmcnt(6)
	v_mfma_f32_32x32x16_bf16 v[64:79], v[176:179], v[188:191], v[64:79]
	v_exp_f32_e32 v96, v96
	v_exp_f32_e32 v97, v97
	v_exp_f32_e32 v98, v98
	v_add_f32_e32 v0, v96, v0
	v_exp_f32_e32 v99, v99
	s_waitcnt lgkmcnt(4)
	v_mfma_f32_32x32x16_bf16 v[64:79], v[180:183], v[192:195], v[64:79]
	ds_read_b64_tr_b16 v[80:81], v238 offset:8192
	ds_read_b64_tr_b16 v[82:83], v238 offset:8704
	ds_read_b64_tr_b16 v[84:85], v238 offset:9216
	ds_read_b64_tr_b16 v[86:87], v238 offset:9728
	v_add_f32_e32 v0, v97, v0
	v_exp_f32_e32 v100, v100
	v_add_f32_e32 v0, v98, v0
	v_exp_f32_e32 v101, v101
	v_add_f32_e32 v0, v99, v0
	s_waitcnt lgkmcnt(6)
	v_mfma_f32_32x32x16_bf16 v[48:63], v[240:243], v[188:191], v[48:63]
	v_exp_f32_e32 v102, v102
	v_add_f32_e32 v0, v100, v0
	v_exp_f32_e32 v103, v103
	v_add_f32_e32 v0, v101, v0
	v_exp_f32_e32 v104, v104
	s_waitcnt lgkmcnt(4)
	v_mfma_f32_32x32x16_bf16 v[48:63], v[244:247], v[192:195], v[48:63]
	ds_read_b64_tr_b16 v[176:177], v238 offset:12288
	ds_read_b64_tr_b16 v[178:179], v238 offset:12800
	ds_read_b64_tr_b16 v[180:181], v238 offset:13312
	ds_read_b64_tr_b16 v[182:183], v238 offset:13824
	v_add_f32_e32 v0, v102, v0
	v_exp_f32_e32 v105, v105
	v_add_f32_e32 v0, v103, v0
	v_exp_f32_e32 v106, v106
	v_add_f32_e32 v0, v104, v0
	s_waitcnt lgkmcnt(6)
	v_mfma_f32_32x32x16_bf16 v[32:47], v[80:83], v[188:191], v[32:47]
	v_exp_f32_e32 v107, v107
	v_add_f32_e32 v0, v105, v0
	v_exp_f32_e32 v108, v108
	v_add_f32_e32 v0, v106, v0
	v_exp_f32_e32 v109, v109
	s_waitcnt lgkmcnt(4)
	v_mfma_f32_32x32x16_bf16 v[32:47], v[84:87], v[192:195], v[32:47]
	ds_read_b64_tr_b16 v[240:241], v238 offset:2048
	ds_read_b64_tr_b16 v[242:243], v238 offset:2560
	ds_read_b64_tr_b16 v[244:245], v238 offset:3072
	ds_read_b64_tr_b16 v[246:247], v238 offset:3584
	v_add_f32_e32 v0, v107, v0
	v_exp_f32_e32 v110, v110
	v_add_f32_e32 v0, v108, v0
	v_exp_f32_e32 v111, v111
	v_add_f32_e32 v0, v109, v0
	s_waitcnt lgkmcnt(6)
	v_mfma_f32_32x32x16_bf16 v[16:31], v[176:179], v[188:191], v[16:31]
	v_add_f32_e32 v0, v110, v0
	v_add_f32_e32 v0, v111, v0
	v_cvt_pk_bf16_f32 v196, v96, v97
	v_cvt_pk_bf16_f32 v197, v98, v99
	v_cvt_pk_bf16_f32 v198, v100, v101
	s_waitcnt lgkmcnt(4)
	v_mfma_f32_32x32x16_bf16 v[16:31], v[180:183], v[192:195], v[16:31]
	ds_read_b64_tr_b16 v[80:81], v238 offset:6144
	ds_read_b64_tr_b16 v[82:83], v238 offset:6656
	ds_read_b64_tr_b16 v[84:85], v238 offset:7168
	ds_read_b64_tr_b16 v[86:87], v238 offset:7680
	v_cvt_pk_bf16_f32 v199, v102, v103
	v_cvt_pk_bf16_f32 v200, v104, v105
	v_cvt_pk_bf16_f32 v201, v106, v107
	v_cvt_pk_bf16_f32 v202, v108, v109
	v_cvt_pk_bf16_f32 v203, v110, v111
	s_nop 1
	s_waitcnt lgkmcnt(6)
	v_mfma_f32_32x32x16_bf16 v[64:79], v[240:243], v[196:199], v[64:79]
	s_waitcnt lgkmcnt(4)
	v_mfma_f32_32x32x16_bf16 v[64:79], v[244:247], v[200:203], v[64:79]
	ds_read_b64_tr_b16 v[176:177], v238 offset:10240
	ds_read_b64_tr_b16 v[178:179], v238 offset:10752
	ds_read_b64_tr_b16 v[180:181], v238 offset:11264
	ds_read_b64_tr_b16 v[182:183], v238 offset:11776
	s_waitcnt lgkmcnt(6)
	v_mfma_f32_32x32x16_bf16 v[48:63], v[80:83], v[196:199], v[48:63]
	s_waitcnt lgkmcnt(4)
	v_mfma_f32_32x32x16_bf16 v[48:63], v[84:87], v[200:203], v[48:63]
	ds_read_b64_tr_b16 v[240:241], v238 offset:14336
	ds_read_b64_tr_b16 v[242:243], v238 offset:14848
	ds_read_b64_tr_b16 v[244:245], v238 offset:15360
	ds_read_b64_tr_b16 v[246:247], v238 offset:15872
	s_waitcnt lgkmcnt(6)
	v_mfma_f32_32x32x16_bf16 v[32:47], v[176:179], v[196:199], v[32:47]
	s_waitcnt lgkmcnt(4)
	v_mfma_f32_32x32x16_bf16 v[32:47], v[180:183], v[200:203], v[32:47]
	s_waitcnt lgkmcnt(2)
	v_mfma_f32_32x32x16_bf16 v[16:31], v[240:243], v[196:199], v[16:31]
	s_waitcnt lgkmcnt(0)
	v_mfma_f32_32x32x16_bf16 v[16:31], v[244:247], v[200:203], v[16:31]

.LBB0_309:
	s_and_b64 vcc, exec, s[40:41]
	s_cbranch_vccz .Lat_O1
	ds_read_b64_tr_b16 v[2:3], v238
	ds_read_b64_tr_b16 v[4:5], v238 offset:512
	ds_read_b64_tr_b16 v[6:7], v238 offset:1024
	ds_read_b64_tr_b16 v[8:9], v238 offset:1536
	ds_read_b64_tr_b16 v[240:241], v238 offset:2048
	ds_read_b64_tr_b16 v[242:243], v238 offset:2560
	ds_read_b64_tr_b16 v[244:245], v238 offset:3072
	ds_read_b64_tr_b16 v[246:247], v238 offset:3584
	s_waitcnt lgkmcnt(6)
	v_mfma_f32_32x32x16_bf16 v[64:79], v[2:5], v[188:191], v[64:79]
	s_waitcnt lgkmcnt(4)
	v_mfma_f32_32x32x16_bf16 v[64:79], v[6:9], v[192:195], v[64:79]
	ds_read_b64_tr_b16 v[2:3], v238 offset:4096
	ds_read_b64_tr_b16 v[4:5], v238 offset:4608
	ds_read_b64_tr_b16 v[6:7], v238 offset:5120
	ds_read_b64_tr_b16 v[8:9], v238 offset:5632
	s_waitcnt lgkmcnt(6)
	v_mfma_f32_32x32x16_bf16 v[64:79], v[240:243], v[196:199], v[64:79]
	s_waitcnt lgkmcnt(4)
	v_mfma_f32_32x32x16_bf16 v[64:79], v[244:247], v[200:203], v[64:79]
	ds_read_b64_tr_b16 v[240:241], v238 offset:6144
	ds_read_b64_tr_b16 v[242:243], v238 offset:6656
	ds_read_b64_tr_b16 v[244:245], v238 offset:7168
	ds_read_b64_tr_b16 v[246:247], v238 offset:7680
	s_waitcnt lgkmcnt(6)
	v_mfma_f32_32x32x16_bf16 v[48:63], v[2:5], v[188:191], v[48:63]
	s_waitcnt lgkmcnt(4)
	v_mfma_f32_32x32x16_bf16 v[48:63], v[6:9], v[192:195], v[48:63]
	ds_read_b64_tr_b16 v[2:3], v238 offset:8192
	ds_read_b64_tr_b16 v[4:5], v238 offset:8704
	ds_read_b64_tr_b16 v[6:7], v238 offset:9216
	ds_read_b64_tr_b16 v[8:9], v238 offset:9728
	s_waitcnt lgkmcnt(6)
	v_mfma_f32_32x32x16_bf16 v[48:63], v[240:243], v[196:199], v[48:63]
	s_waitcnt lgkmcnt(4)
	v_mfma_f32_32x32x16_bf16 v[48:63], v[244:247], v[200:203], v[48:63]
	ds_read_b64_tr_b16 v[240:241], v238 offset:10240
	ds_read_b64_tr_b16 v[242:243], v238 offset:10752
	ds_read_b64_tr_b16 v[244:245], v238 offset:11264
	ds_read_b64_tr_b16 v[246:247], v238 offset:11776
	s_waitcnt lgkmcnt(6)
	v_mfma_f32_32x32x16_bf16 v[32:47], v[2:5], v[188:191], v[32:47]
	s_waitcnt lgkmcnt(4)
	v_mfma_f32_32x32x16_bf16 v[32:47], v[6:9], v[192:195], v[32:47]
	ds_read_b64_tr_b16 v[2:3], v238 offset:12288
	ds_read_b64_tr_b16 v[4:5], v238 offset:12800
	ds_read_b64_tr_b16 v[6:7], v238 offset:13312
	ds_read_b64_tr_b16 v[8:9], v238 offset:13824
	s_waitcnt lgkmcnt(6)
	v_mfma_f32_32x32x16_bf16 v[32:47], v[240:243], v[196:199], v[32:47]
	s_waitcnt lgkmcnt(4)
	v_mfma_f32_32x32x16_bf16 v[32:47], v[244:247], v[200:203], v[32:47]
	ds_read_b64_tr_b16 v[240:241], v238 offset:14336
	ds_read_b64_tr_b16 v[242:243], v238 offset:14848
	ds_read_b64_tr_b16 v[244:245], v238 offset:15360
	ds_read_b64_tr_b16 v[246:247], v238 offset:15872
	s_waitcnt lgkmcnt(6)
	v_mfma_f32_32x32x16_bf16 v[16:31], v[2:5], v[188:191], v[16:31]
	s_waitcnt lgkmcnt(4)
	v_mfma_f32_32x32x16_bf16 v[16:31], v[6:9], v[192:195], v[16:31]
	s_waitcnt lgkmcnt(2)
	v_mfma_f32_32x32x16_bf16 v[16:31], v[240:243], v[196:199], v[16:31]
	s_waitcnt lgkmcnt(0)
	v_mfma_f32_32x32x16_bf16 v[16:31], v[244:247], v[200:203], v[16:31]
	s_and_b64 vcc, exec, s[40:41]
	s_cbranch_vccz .LBB0_323

.LBB0_312:
	v_exp_f32_e32 v112, v112
	v_exp_f32_e32 v113, v113
	v_exp_f32_e32 v189, v128
	v_exp_f32_e32 v129, v129
	v_add_f32_e32 v128, 0, v112
	v_add_f32_e32 v128, v113, v128
	v_exp_f32_e32 v114, v114
	v_add_f32_e32 v128, v189, v128
	v_exp_f32_e32 v115, v115
	v_add_f32_e32 v128, v129, v128
	v_exp_f32_e32 v130, v130
	v_exp_f32_e32 v131, v131
	v_add_f32_e32 v128, v114, v128
	v_add_f32_e32 v128, v115, v128
	v_exp_f32_e32 v116, v116
	v_add_f32_e32 v128, v130, v128
	v_exp_f32_e32 v117, v117
	v_add_f32_e32 v128, v131, v128
	v_exp_f32_e32 v132, v132
	v_exp_f32_e32 v133, v133
	v_add_f32_e32 v128, v116, v128
	v_add_f32_e32 v128, v117, v128
	v_exp_f32_e32 v118, v118
	v_add_f32_e32 v128, v132, v128
	v_exp_f32_e32 v119, v119
	v_add_f32_e32 v128, v133, v128
	v_exp_f32_e32 v134, v134
	v_exp_f32_e32 v135, v135
	v_add_f32_e32 v128, v118, v128
	v_add_f32_e32 v128, v119, v128
	v_exp_f32_e32 v120, v120
	v_add_f32_e32 v128, v134, v128
	v_exp_f32_e32 v121, v121
	v_add_f32_e32 v128, v135, v128
	v_exp_f32_e32 v136, v136
	v_exp_f32_e32 v137, v137
	v_add_f32_e32 v128, v120, v128
	v_add_f32_e32 v128, v121, v128
	v_exp_f32_e32 v122, v122
	v_add_f32_e32 v128, v136, v128
	v_exp_f32_e32 v123, v123
	v_add_f32_e32 v128, v137, v128
	v_exp_f32_e32 v138, v138
	v_exp_f32_e32 v139, v139
	v_add_f32_e32 v128, v122, v128
	v_add_f32_e32 v128, v123, v128
	v_exp_f32_e32 v124, v124
	v_add_f32_e32 v128, v138, v128
	v_exp_f32_e32 v125, v125
	v_add_f32_e32 v128, v139, v128
	v_exp_f32_e32 v140, v140
	v_exp_f32_e32 v141, v141
	v_add_f32_e32 v128, v124, v128
	v_add_f32_e32 v128, v125, v128
	v_exp_f32_e32 v126, v126
	v_add_f32_e32 v128, v140, v128
	v_exp_f32_e32 v127, v127
	v_add_f32_e32 v128, v141, v128
	v_exp_f32_e32 v142, v142
	v_exp_f32_e32 v143, v143
	v_add_f32_e32 v128, v126, v128
	v_add_f32_e32 v128, v127, v128
	v_add_f32_e32 v128, v142, v128
	v_add_f32_e32 v128, v143, v128
	v_cvt_pk_bf16_f32 v112, v112, v113
	v_cvt_pk_bf16_f32 v113, v114, v115
	v_cvt_pk_bf16_f32 v114, v116, v117
	v_cvt_pk_bf16_f32 v115, v118, v119
	v_cvt_pk_bf16_f32 v116, v120, v121
	v_cvt_pk_bf16_f32 v117, v122, v123
	v_cvt_pk_bf16_f32 v118, v124, v125
	v_cvt_pk_bf16_f32 v119, v126, v127
	v_cvt_pk_bf16_f32 v120, v189, v129
	v_cvt_pk_bf16_f32 v121, v130, v131
	v_cvt_pk_bf16_f32 v122, v132, v133
	v_cvt_pk_bf16_f32 v123, v134, v135
	v_cvt_pk_bf16_f32 v124, v136, v137
	v_cvt_pk_bf16_f32 v125, v138, v139
	v_cvt_pk_bf16_f32 v126, v140, v141
	s_and_b64 vcc, exec, s[36:37]
	v_cvt_pk_bf16_f32 v127, v142, v143
	s_cbranch_vccnz .LBB0_314
	ds_read_b64_tr_b16 v[130:131], v188 offset:2048
	ds_read_b64_tr_b16 v[132:133], v188 offset:2560
	ds_read_b64_tr_b16 v[134:135], v188 offset:3072
	ds_read_b64_tr_b16 v[136:137], v188 offset:3584
	s_waitcnt lgkmcnt(6)
	v_mfma_f32_32x32x16_bf16 v[64:79], v[2:5], v[112:115], v[64:79]
	s_waitcnt lgkmcnt(4)
	v_mfma_f32_32x32x16_bf16 v[64:79], v[6:9], v[116:119], v[64:79]
	ds_read_b64_tr_b16 v[2:3], v188 offset:4096
	ds_read_b64_tr_b16 v[4:5], v188 offset:4608
	ds_read_b64_tr_b16 v[6:7], v188 offset:5120
	ds_read_b64_tr_b16 v[8:9], v188 offset:5632
	s_waitcnt lgkmcnt(6)
	v_mfma_f32_32x32x16_bf16 v[64:79], v[130:133], v[120:123], v[64:79]
	s_waitcnt lgkmcnt(4)
	v_mfma_f32_32x32x16_bf16 v[64:79], v[134:137], v[124:127], v[64:79]
	ds_read_b64_tr_b16 v[130:131], v188 offset:6144
	ds_read_b64_tr_b16 v[132:133], v188 offset:6656
	ds_read_b64_tr_b16 v[134:135], v188 offset:7168
	ds_read_b64_tr_b16 v[136:137], v188 offset:7680
	s_waitcnt lgkmcnt(6)
	v_mfma_f32_32x32x16_bf16 v[48:63], v[2:5], v[112:115], v[48:63]
	s_waitcnt lgkmcnt(4)
	v_mfma_f32_32x32x16_bf16 v[48:63], v[6:9], v[116:119], v[48:63]
	ds_read_b64_tr_b16 v[2:3], v188 offset:8192
	ds_read_b64_tr_b16 v[4:5], v188 offset:8704
	ds_read_b64_tr_b16 v[6:7], v188 offset:9216
	ds_read_b64_tr_b16 v[8:9], v188 offset:9728
	s_waitcnt lgkmcnt(6)
	v_mfma_f32_32x32x16_bf16 v[48:63], v[130:133], v[120:123], v[48:63]
	s_waitcnt lgkmcnt(4)
	v_mfma_f32_32x32x16_bf16 v[48:63], v[134:137], v[124:127], v[48:63]
	ds_read_b64_tr_b16 v[130:131], v188 offset:10240
	ds_read_b64_tr_b16 v[132:133], v188 offset:10752
	ds_read_b64_tr_b16 v[134:135], v188 offset:11264
	ds_read_b64_tr_b16 v[136:137], v188 offset:11776
	s_waitcnt lgkmcnt(6)
	v_mfma_f32_32x32x16_bf16 v[32:47], v[2:5], v[112:115], v[32:47]
	s_waitcnt lgkmcnt(4)
	v_mfma_f32_32x32x16_bf16 v[32:47], v[6:9], v[116:119], v[32:47]
	ds_read_b64_tr_b16 v[2:3], v188 offset:12288
	ds_read_b64_tr_b16 v[4:5], v188 offset:12800
	ds_read_b64_tr_b16 v[6:7], v188 offset:13312
	ds_read_b64_tr_b16 v[8:9], v188 offset:13824
	s_waitcnt lgkmcnt(6)
	v_mfma_f32_32x32x16_bf16 v[32:47], v[130:133], v[120:123], v[32:47]
	s_waitcnt lgkmcnt(4)
	v_mfma_f32_32x32x16_bf16 v[32:47], v[134:137], v[124:127], v[32:47]
	ds_read_b64_tr_b16 v[130:131], v188 offset:14336
	ds_read_b64_tr_b16 v[132:133], v188 offset:14848
	ds_read_b64_tr_b16 v[134:135], v188 offset:15360
	ds_read_b64_tr_b16 v[136:137], v188 offset:15872
	s_waitcnt lgkmcnt(6)
	v_mfma_f32_32x32x16_bf16 v[16:31], v[2:5], v[112:115], v[16:31]
	s_waitcnt lgkmcnt(4)
	v_mfma_f32_32x32x16_bf16 v[16:31], v[6:9], v[116:119], v[16:31]
	s_waitcnt lgkmcnt(2)
	v_mfma_f32_32x32x16_bf16 v[16:31], v[130:133], v[120:123], v[16:31]
	s_waitcnt lgkmcnt(0)
	v_mfma_f32_32x32x16_bf16 v[16:31], v[134:137], v[124:127], v[16:31]

.LBB0_323:
	v_add_u32_e32 v188, s57, v233
	ds_read_b64_tr_b16 v[2:3], v188
	ds_read_b64_tr_b16 v[4:5], v188 offset:512
	ds_read_b64_tr_b16 v[6:7], v188 offset:1024
	ds_read_b64_tr_b16 v[8:9], v188 offset:1536
	ds_read_b128 v[80:83], v229
	ds_read_b128 v[96:99], v229 offset:4096
	ds_read_b128 v[240:243], v230
	ds_read_b128 v[244:247], v230 offset:4096
	ds_read_b128 v[248:251], v231
	v_exp_f32_e32 v112, v112
	v_exp_f32_e32 v113, v113
	v_exp_f32_e32 v114, v114
	v_add_f32_e32 v239, 0, v112
	v_exp_f32_e32 v115, v115
	v_add_f32_e32 v239, v113, v239
	v_exp_f32_e32 v116, v116
	v_add_f32_e32 v239, v114, v239
	s_waitcnt lgkmcnt(4)
	v_mfma_f32_32x32x16_bf16 v[80:95], v[80:83], v[160:163], 0
	v_exp_f32_e32 v117, v117
	v_add_f32_e32 v239, v115, v239
	v_exp_f32_e32 v118, v118
	v_add_f32_e32 v239, v116, v239
	s_waitcnt lgkmcnt(3)
	v_mfma_f32_32x32x16_bf16 v[96:111], v[96:99], v[160:163], 0
	v_exp_f32_e32 v119, v119
	v_add_f32_e32 v239, v117, v239
	v_exp_f32_e32 v120, v120
	v_add_f32_e32 v239, v118, v239
	s_waitcnt lgkmcnt(2)
	v_mfma_f32_32x32x16_bf16 v[80:95], v[240:243], v[164:167], v[80:95]
	ds_read_b128 v[240:243], v231 offset:4096
	v_exp_f32_e32 v121, v121
	v_add_f32_e32 v239, v119, v239
	v_exp_f32_e32 v122, v122
	v_add_f32_e32 v239, v120, v239
	s_waitcnt lgkmcnt(2)
	v_mfma_f32_32x32x16_bf16 v[96:111], v[244:247], v[164:167], v[96:111]
	ds_read_b128 v[244:247], v232
	v_exp_f32_e32 v123, v123
	v_add_f32_e32 v239, v121, v239
	v_exp_f32_e32 v124, v124
	v_add_f32_e32 v239, v122, v239
	s_waitcnt lgkmcnt(2)
	v_mfma_f32_32x32x16_bf16 v[80:95], v[248:251], v[168:171], v[80:95]
	ds_read_b128 v[248:251], v232 offset:4096
	v_exp_f32_e32 v125, v125
	v_add_f32_e32 v239, v123, v239
	v_exp_f32_e32 v126, v126
	v_add_f32_e32 v239, v124, v239
	s_waitcnt lgkmcnt(2)
	v_mfma_f32_32x32x16_bf16 v[96:111], v[240:243], v[168:171], v[96:111]
	v_exp_f32_e32 v127, v127
	v_add_f32_e32 v239, v125, v239
	v_add_f32_e32 v239, v126, v239
	v_add_f32_e32 v239, v127, v239
	s_waitcnt lgkmcnt(1)
	v_mfma_f32_32x32x16_bf16 v[80:95], v[244:247], v[172:175], v[80:95]
	v_cvt_pk_bf16_f32 v112, v112, v113
	v_cvt_pk_bf16_f32 v113, v114, v115
	v_cvt_pk_bf16_f32 v114, v116, v117
	v_cvt_pk_bf16_f32 v115, v118, v119
	s_waitcnt lgkmcnt(0)
	v_mfma_f32_32x32x16_bf16 v[96:111], v[248:251], v[172:175], v[96:111]
	v_cvt_pk_bf16_f32 v116, v120, v121
	v_cvt_pk_bf16_f32 v117, v122, v123
	v_cvt_pk_bf16_f32 v118, v124, v125
	v_cvt_pk_bf16_f32 v119, v126, v127
	ds_read_b64_tr_b16 v[240:241], v188 offset:4096
	ds_read_b64_tr_b16 v[242:243], v188 offset:4608
	ds_read_b64_tr_b16 v[244:245], v188 offset:5120
	ds_read_b64_tr_b16 v[246:247], v188 offset:5632
	s_waitcnt lgkmcnt(6)
	v_mfma_f32_32x32x16_bf16 v[64:79], v[2:5], v[112:115], v[64:79]
	v_exp_f32_e32 v128, v128
	v_exp_f32_e32 v129, v129
	v_exp_f32_e32 v130, v130
	v_add_f32_e32 v239, v128, v239
	v_exp_f32_e32 v131, v131
	s_waitcnt lgkmcnt(4)
	v_mfma_f32_32x32x16_bf16 v[64:79], v[6:9], v[116:119], v[64:79]
	ds_read_b64_tr_b16 v[176:177], v188 offset:8192
	ds_read_b64_tr_b16 v[178:179], v188 offset:8704
	ds_read_b64_tr_b16 v[180:181], v188 offset:9216
	ds_read_b64_tr_b16 v[182:183], v188 offset:9728
	v_add_f32_e32 v239, v129, v239
	v_exp_f32_e32 v132, v132
	v_add_f32_e32 v239, v130, v239
	v_exp_f32_e32 v133, v133
	v_add_f32_e32 v239, v131, v239
	s_waitcnt lgkmcnt(6)
	v_mfma_f32_32x32x16_bf16 v[48:63], v[240:243], v[112:115], v[48:63]
	v_exp_f32_e32 v134, v134
	v_add_f32_e32 v239, v132, v239
	v_exp_f32_e32 v135, v135
	v_add_f32_e32 v239, v133, v239
	v_exp_f32_e32 v136, v136
	s_waitcnt lgkmcnt(4)
	v_mfma_f32_32x32x16_bf16 v[48:63], v[244:247], v[116:119], v[48:63]
	ds_read_b64_tr_b16 v[2:3], v188 offset:12288
	ds_read_b64_tr_b16 v[4:5], v188 offset:12800
	ds_read_b64_tr_b16 v[6:7], v188 offset:13312
	ds_read_b64_tr_b16 v[8:9], v188 offset:13824
	v_add_f32_e32 v239, v134, v239
	v_exp_f32_e32 v137, v137
	v_add_f32_e32 v239, v135, v239
	v_exp_f32_e32 v138, v138
	v_add_f32_e32 v239, v136, v239
	s_waitcnt lgkmcnt(6)
	v_mfma_f32_32x32x16_bf16 v[32:47], v[176:179], v[112:115], v[32:47]
	v_exp_f32_e32 v139, v139
	v_add_f32_e32 v239, v137, v239
	v_exp_f32_e32 v140, v140
	v_add_f32_e32 v239, v138, v239
	v_exp_f32_e32 v141, v141
	s_waitcnt lgkmcnt(4)
	v_mfma_f32_32x32x16_bf16 v[32:47], v[180:183], v[116:119], v[32:47]
	ds_read_b64_tr_b16 v[240:241], v188 offset:2048
	ds_read_b64_tr_b16 v[242:243], v188 offset:2560
	ds_read_b64_tr_b16 v[244:245], v188 offset:3072
	ds_read_b64_tr_b16 v[246:247], v188 offset:3584
	v_add_f32_e32 v239, v139, v239
	v_exp_f32_e32 v142, v142
	v_add_f32_e32 v239, v140, v239
	v_exp_f32_e32 v143, v143
	v_add_f32_e32 v239, v141, v239
	s_waitcnt lgkmcnt(6)
	v_mfma_f32_32x32x16_bf16 v[16:31], v[2:5], v[112:115], v[16:31]
	v_add_f32_e32 v239, v142, v239
	v_add_f32_e32 v239, v143, v239
	v_cvt_pk_bf16_f32 v120, v128, v129
	v_cvt_pk_bf16_f32 v121, v130, v131
	v_cvt_pk_bf16_f32 v122, v132, v133
	s_waitcnt lgkmcnt(4)
	v_mfma_f32_32x32x16_bf16 v[16:31], v[6:9], v[116:119], v[16:31]
	ds_read_b64_tr_b16 v[176:177], v188 offset:6144
	ds_read_b64_tr_b16 v[178:179], v188 offset:6656
	ds_read_b64_tr_b16 v[180:181], v188 offset:7168
	ds_read_b64_tr_b16 v[182:183], v188 offset:7680
	v_cvt_pk_bf16_f32 v123, v134, v135
	v_cvt_pk_bf16_f32 v124, v136, v137
	v_cvt_pk_bf16_f32 v125, v138, v139
	v_cvt_pk_bf16_f32 v126, v140, v141
	v_cvt_pk_bf16_f32 v127, v142, v143
	s_nop 1
	s_waitcnt lgkmcnt(6)
	v_mfma_f32_32x32x16_bf16 v[64:79], v[240:243], v[120:123], v[64:79]
	v_mov_b32_e32 v128, v239
	s_waitcnt lgkmcnt(4)
	v_mfma_f32_32x32x16_bf16 v[64:79], v[244:247], v[124:127], v[64:79]
	ds_read_b64_tr_b16 v[2:3], v188 offset:10240
	ds_read_b64_tr_b16 v[4:5], v188 offset:10752
	ds_read_b64_tr_b16 v[6:7], v188 offset:11264
	ds_read_b64_tr_b16 v[8:9], v188 offset:11776
	s_waitcnt lgkmcnt(6)
	v_mfma_f32_32x32x16_bf16 v[48:63], v[176:179], v[120:123], v[48:63]
	s_waitcnt lgkmcnt(4)
	v_mfma_f32_32x32x16_bf16 v[48:63], v[180:183], v[124:127], v[48:63]
	ds_read_b64_tr_b16 v[240:241], v188 offset:14336
	ds_read_b64_tr_b16 v[242:243], v188 offset:14848
	ds_read_b64_tr_b16 v[244:245], v188 offset:15360
	ds_read_b64_tr_b16 v[246:247], v188 offset:15872
	s_waitcnt lgkmcnt(6)
	v_mfma_f32_32x32x16_bf16 v[32:47], v[2:5], v[120:123], v[32:47]
	s_waitcnt lgkmcnt(4)
	v_mfma_f32_32x32x16_bf16 v[32:47], v[6:9], v[124:127], v[32:47]
	s_waitcnt lgkmcnt(2)
	v_mfma_f32_32x32x16_bf16 v[16:31], v[240:243], v[120:123], v[16:31]
	s_waitcnt lgkmcnt(0)
	v_mfma_f32_32x32x16_bf16 v[16:31], v[244:247], v[124:127], v[16:31]
	s_branch .LBB0_314
.Lat_O1:
	ds_read_b64_tr_b16 v[2:3], v238
	ds_read_b64_tr_b16 v[4:5], v238 offset:512
	ds_read_b64_tr_b16 v[6:7], v238 offset:1024
	ds_read_b64_tr_b16 v[8:9], v238 offset:1536
	ds_read_b64_tr_b16 v[240:241], v238 offset:2048
	ds_read_b64_tr_b16 v[242:243], v238 offset:2560
	ds_read_b64_tr_b16 v[244:245], v238 offset:3072
	ds_read_b64_tr_b16 v[246:247], v238 offset:3584
	v_exp_f32_e32 v112, v112
	v_exp_f32_e32 v113, v113
	v_exp_f32_e32 v114, v114
	v_add_f32_e32 v239, 0, v112
	v_exp_f32_e32 v115, v115
	v_add_f32_e32 v239, v113, v239
	v_exp_f32_e32 v116, v116
	v_add_f32_e32 v239, v114, v239
	v_exp_f32_e32 v117, v117
	v_add_f32_e32 v239, v115, v239
	s_waitcnt lgkmcnt(6)
	v_mfma_f32_32x32x16_bf16 v[64:79], v[2:5], v[188:191], v[64:79]
	v_exp_f32_e32 v118, v118
	v_add_f32_e32 v239, v116, v239
	v_exp_f32_e32 v119, v119
	s_waitcnt lgkmcnt(4)
	v_mfma_f32_32x32x16_bf16 v[64:79], v[6:9], v[192:195], v[64:79]
	ds_read_b64_tr_b16 v[80:81], v238 offset:4096
	ds_read_b64_tr_b16 v[82:83], v238 offset:4608
	ds_read_b64_tr_b16 v[84:85], v238 offset:5120
	ds_read_b64_tr_b16 v[86:87], v238 offset:5632
	v_add_f32_e32 v239, v117, v239
	v_exp_f32_e32 v120, v120
	v_add_f32_e32 v239, v118, v239
	s_waitcnt lgkmcnt(6)
	v_mfma_f32_32x32x16_bf16 v[64:79], v[240:243], v[196:199], v[64:79]
	v_exp_f32_e32 v121, v121
	v_add_f32_e32 v239, v119, v239
	v_exp_f32_e32 v122, v122
	s_waitcnt lgkmcnt(4)
	v_mfma_f32_32x32x16_bf16 v[64:79], v[244:247], v[200:203], v[64:79]
	ds_read_b64_tr_b16 v[2:3], v238 offset:6144
	ds_read_b64_tr_b16 v[4:5], v238 offset:6656
	ds_read_b64_tr_b16 v[6:7], v238 offset:7168
	ds_read_b64_tr_b16 v[8:9], v238 offset:7680
	v_add_f32_e32 v239, v120, v239
	v_exp_f32_e32 v123, v123
	v_add_f32_e32 v239, v121, v239
	s_waitcnt lgkmcnt(6)
	v_mfma_f32_32x32x16_bf16 v[48:63], v[80:83], v[188:191], v[48:63]
	v_exp_f32_e32 v124, v124
	v_add_f32_e32 v239, v122, v239
	v_exp_f32_e32 v125, v125
	s_waitcnt lgkmcnt(4)
	v_mfma_f32_32x32x16_bf16 v[48:63], v[84:87], v[192:195], v[48:63]
	ds_read_b64_tr_b16 v[240:241], v238 offset:8192
	ds_read_b64_tr_b16 v[242:243], v238 offset:8704
	ds_read_b64_tr_b16 v[244:245], v238 offset:9216
	ds_read_b64_tr_b16 v[246:247], v238 offset:9728
	v_add_f32_e32 v239, v123, v239
	v_exp_f32_e32 v126, v126
	v_add_f32_e32 v239, v124, v239
	s_waitcnt lgkmcnt(6)
	v_mfma_f32_32x32x16_bf16 v[48:63], v[2:5], v[196:199], v[48:63]
	v_exp_f32_e32 v127, v127
	v_add_f32_e32 v239, v125, v239
	v_add_f32_e32 v239, v126, v239
	s_waitcnt lgkmcnt(4)
	v_mfma_f32_32x32x16_bf16 v[48:63], v[6:9], v[200:203], v[48:63]
	ds_read_b64_tr_b16 v[80:81], v238 offset:10240
	ds_read_b64_tr_b16 v[82:83], v238 offset:10752
	ds_read_b64_tr_b16 v[84:85], v238 offset:11264
	ds_read_b64_tr_b16 v[86:87], v238 offset:11776
	v_add_f32_e32 v239, v127, v239
	v_cvt_pk_bf16_f32 v112, v112, v113
	v_cvt_pk_bf16_f32 v113, v114, v115
	s_waitcnt lgkmcnt(6)
	v_mfma_f32_32x32x16_bf16 v[32:47], v[240:243], v[188:191], v[32:47]
	v_cvt_pk_bf16_f32 v114, v116, v117
	v_cvt_pk_bf16_f32 v115, v118, v119
	v_cvt_pk_bf16_f32 v116, v120, v121
	s_waitcnt lgkmcnt(4)
	v_mfma_f32_32x32x16_bf16 v[32:47], v[244:247], v[192:195], v[32:47]
	ds_read_b64_tr_b16 v[2:3], v238 offset:12288
	ds_read_b64_tr_b16 v[4:5], v238 offset:12800
	ds_read_b64_tr_b16 v[6:7], v238 offset:13312
	ds_read_b64_tr_b16 v[8:9], v238 offset:13824
	v_cvt_pk_bf16_f32 v117, v122, v123
	v_cvt_pk_bf16_f32 v118, v124, v125
	v_cvt_pk_bf16_f32 v119, v126, v127
	s_waitcnt lgkmcnt(6)
	v_mfma_f32_32x32x16_bf16 v[32:47], v[80:83], v[196:199], v[32:47]
	v_exp_f32_e32 v128, v128
	v_exp_f32_e32 v129, v129
	v_exp_f32_e32 v130, v130
	s_waitcnt lgkmcnt(4)
	v_mfma_f32_32x32x16_bf16 v[32:47], v[84:87], v[200:203], v[32:47]
	ds_read_b64_tr_b16 v[240:241], v238 offset:14336
	ds_read_b64_tr_b16 v[242:243], v238 offset:14848
	ds_read_b64_tr_b16 v[244:245], v238 offset:15360
	ds_read_b64_tr_b16 v[246:247], v238 offset:15872
	v_add_f32_e32 v239, v128, v239
	v_exp_f32_e32 v131, v131
	v_add_f32_e32 v239, v129, v239
	s_waitcnt lgkmcnt(6)
	v_mfma_f32_32x32x16_bf16 v[16:31], v[2:5], v[188:191], v[16:31]
	v_exp_f32_e32 v132, v132
	v_add_f32_e32 v239, v130, v239
	v_exp_f32_e32 v133, v133
	s_waitcnt lgkmcnt(4)
	v_mfma_f32_32x32x16_bf16 v[16:31], v[6:9], v[192:195], v[16:31]
	v_add_f32_e32 v239, v131, v239
	v_exp_f32_e32 v134, v134
	v_add_f32_e32 v239, v132, v239
	s_waitcnt lgkmcnt(2)
	v_mfma_f32_32x32x16_bf16 v[16:31], v[240:243], v[196:199], v[16:31]
	v_exp_f32_e32 v135, v135
	v_add_f32_e32 v239, v133, v239
	v_exp_f32_e32 v136, v136
	s_waitcnt lgkmcnt(0)
	v_mfma_f32_32x32x16_bf16 v[16:31], v[244:247], v[200:203], v[16:31]
	v_add_f32_e32 v239, v134, v239
	v_exp_f32_e32 v137, v137
	v_add_f32_e32 v239, v135, v239
	ds_read_b128 v[80:83], v229
	ds_read_b128 v[96:99], v229 offset:4096
	ds_read_b128 v[240:243], v230
	ds_read_b128 v[244:247], v230 offset:4096
	ds_read_b128 v[248:251], v231
	v_exp_f32_e32 v138, v138
	v_add_f32_e32 v239, v136, v239
	s_waitcnt lgkmcnt(4)
	v_mfma_f32_32x32x16_bf16 v[80:95], v[80:83], v[160:163], 0
	v_exp_f32_e32 v139, v139
	v_add_f32_e32 v239, v137, v239
	v_exp_f32_e32 v140, v140
	s_waitcnt lgkmcnt(3)
	v_mfma_f32_32x32x16_bf16 v[96:111], v[96:99], v[160:163], 0
	v_add_f32_e32 v239, v138, v239
	v_exp_f32_e32 v141, v141
	v_add_f32_e32 v239, v139, v239
	s_waitcnt lgkmcnt(2)
	v_mfma_f32_32x32x16_bf16 v[80:95], v[240:243], v[164:167], v[80:95]
	ds_read_b128 v[240:243], v231 offset:4096
	v_exp_f32_e32 v142, v142
	v_add_f32_e32 v239, v140, v239
	v_exp_f32_e32 v143, v143
	s_waitcnt lgkmcnt(2)
	v_mfma_f32_32x32x16_bf16 v[96:111], v[244:247], v[164:167], v[96:111]
	ds_read_b128 v[244:247], v232
	v_add_f32_e32 v239, v141, v239
	v_add_f32_e32 v239, v142, v239
	v_add_f32_e32 v239, v143, v239
	s_waitcnt lgkmcnt(2)
	v_mfma_f32_32x32x16_bf16 v[80:95], v[248:251], v[168:171], v[80:95]
	ds_read_b128 v[248:251], v232 offset:4096
	v_cvt_pk_bf16_f32 v120, v128, v129
	v_cvt_pk_bf16_f32 v121, v130, v131
	v_cvt_pk_bf16_f32 v122, v132, v133
	s_waitcnt lgkmcnt(2)
	v_mfma_f32_32x32x16_bf16 v[96:111], v[240:243], v[168:171], v[96:111]
	v_cvt_pk_bf16_f32 v123, v134, v135
	v_cvt_pk_bf16_f32 v124, v136, v137
	s_waitcnt lgkmcnt(1)
	v_mfma_f32_32x32x16_bf16 v[80:95], v[244:247], v[172:175], v[80:95]
	v_cvt_pk_bf16_f32 v125, v138, v139
	v_cvt_pk_bf16_f32 v126, v140, v141
	s_waitcnt lgkmcnt(0)
	v_mfma_f32_32x32x16_bf16 v[96:111], v[248:251], v[172:175], v[96:111]
	v_cvt_pk_bf16_f32 v127, v142, v143
	v_mov_b32_e32 v128, v239
	s_branch .LBB0_314
